# grid barrier: only the XCD leader invalidates L2 (buffer_inv sc1); followers and the panel-exchange acquires invalidate L1 only (buffer_inv sc0)
# speedup vs baseline: 1.0163x; 1.0162x over previous
; __device__ __forceinline__ unsigned xb_ld(unsigned* p)              { return __hip_atomic_load(p, __ATOMIC_RELAXED, __HIP_MEMORY_SCOPE_AGENT); }
; #define XB_SPIN(cond, bar) do { unsigned _sp = 0; while (cond) { \
;     if ((++_sp & 255u) == 0u) { if (xb_ld(&(bar)[XB_TMO])) break; if (_sp > XB_SPIN_CAP) { atomicAdd(&(bar)[XB_TMO], 1u); break; } } } } while (0)
; __device__ __forceinline__ void xcd_barrier(const XcdBarrier& b) {
;     ...
;             XB_SPIN(xb_ld(&bar[XB_XGEN(b.x)]) == gen, bar);
;             __builtin_amdgcn_fence(__ATOMIC_ACQUIRE, "agent");
;             asm volatile("s_waitcnt vmcnt(0)" ::: "memory");
.LBB0_148:
	s_or_b64 exec, exec, s[8:9]
	s_waitcnt vmcnt(0)
	buffer_inv sc0
	s_waitcnt vmcnt(0)

;     __device__ __forceinline__ void fused(Acc& acc, const pg8::Unit& u, int wr, int wc, int fr, int fq, LAS unsigned char* lds, int wid, int lane) const {
;     ...
;         if (wid == 0) {
;             unsigned sp = 0;
;             while ((unsigned)__builtin_amdgcn_readfirstlane(__hip_atomic_load(cnt + 64 * u.pm, __ATOMIC_RELAXED, __HIP_MEMORY_SCOPE_AGENT)) < 32u) { if (++sp > (1u << 20)) break; }
;             __builtin_amdgcn_fence(__ATOMIC_ACQUIRE, "agent");
;         }
.LBB0_970:
	global_load_dword v19, v161, s[4:5] sc1
	s_waitcnt vmcnt(0)
	v_readfirstlane_b32 s8, v19
	s_cmp_gt_u32 s8, 31
	s_cselect_b64 s[8:9], -1, 0
	s_add_i32 s12, s6, 1
	s_cmp_gt_u32 s6, 0xfffff
	s_cselect_b64 s[10:11], -1, 0
	s_or_b64 s[8:9], s[8:9], s[10:11]
	s_andn2_b64 vcc, exec, s[8:9]
	s_mov_b32 s6, s12
	s_cbranch_vccnz .LBB0_970
	buffer_inv sc0

;     __device__ __forceinline__ void fused(Acc& acc, const pg8::Unit& u, int wr, int wc, int fr, int fq, LAS unsigned char* lds, int wid, int lane) const {
;     ...
;         if (wid == 0) {
;             unsigned sp = 0;
;             while ((unsigned)__builtin_amdgcn_readfirstlane(__hip_atomic_load(cnt + 64 * u.pm, __ATOMIC_RELAXED, __HIP_MEMORY_SCOPE_AGENT)) < 32u) { if (++sp > (1u << 20)) break; }
;             __builtin_amdgcn_fence(__ATOMIC_ACQUIRE, "agent");
;         }
.LBB0_1074:
	global_load_dword v18, v161, s[12:13] sc1
	s_waitcnt vmcnt(0)
	v_readfirstlane_b32 s25, v18
	s_cmp_gt_u32 s25, 31
	s_cselect_b64 s[34:35], -1, 0
	s_add_i32 s54, s24, 1
	s_cmp_gt_u32 s24, 0xfffff
	s_cselect_b64 s[24:25], -1, 0
	s_or_b64 s[24:25], s[34:35], s[24:25]
	s_andn2_b64 vcc, exec, s[24:25]
	s_mov_b32 s24, s54
	s_cbranch_vccnz .LBB0_1074
	buffer_inv sc0

; __device__ __forceinline__ unsigned xb_ld(unsigned* p)              { return __hip_atomic_load(p, __ATOMIC_RELAXED, __HIP_MEMORY_SCOPE_AGENT); }
; #define XB_SPIN(cond, bar) do { unsigned _sp = 0; while (cond) { \
;     if ((++_sp & 255u) == 0u) { if (xb_ld(&(bar)[XB_TMO])) break; if (_sp > XB_SPIN_CAP) { atomicAdd(&(bar)[XB_TMO], 1u); break; } } } } while (0)
; __device__ __forceinline__ void xcd_barrier(const XcdBarrier& b) {
;     ...
;             XB_SPIN(xb_ld(&bar[XB_XGEN(b.x)]) == gen, bar);
;             __builtin_amdgcn_fence(__ATOMIC_ACQUIRE, "agent");
;             asm volatile("s_waitcnt vmcnt(0)" ::: "memory");
.LBB0_1173:
	s_or_b64 exec, exec, s[10:11]
	s_waitcnt vmcnt(0)
	buffer_inv sc0
	s_waitcnt vmcnt(0)

;     __device__ __forceinline__ void fused(Acc& acc, const pg8::Unit& u, int wr, int wc, int fr, int fq, LAS unsigned char* lds, int wid, int lane) const {
;     ...
;         if (wid == 0) {
;             unsigned sp = 0;
;             while ((unsigned)__builtin_amdgcn_readfirstlane(__hip_atomic_load(cnt + 64 * u.pm, __ATOMIC_RELAXED, __HIP_MEMORY_SCOPE_AGENT)) < 32u) { if (++sp > (1u << 20)) break; }
;             __builtin_amdgcn_fence(__ATOMIC_ACQUIRE, "agent");
;         }
.LBB0_1332:
	global_load_dword v3, v161, s[6:7] sc1
	s_waitcnt vmcnt(0)
	v_readfirstlane_b32 s9, v3
	s_cmp_gt_u32 s9, 31
	s_cselect_b64 s[10:11], -1, 0
	s_add_i32 s12, s8, 1
	s_cmp_gt_u32 s8, 0xfffff
	s_cselect_b64 s[8:9], -1, 0
	s_or_b64 s[8:9], s[10:11], s[8:9]
	s_andn2_b64 vcc, exec, s[8:9]
	s_mov_b32 s8, s12
	s_cbranch_vccnz .LBB0_1332
	buffer_inv sc0

;     __device__ __forceinline__ void fused(Acc& acc, const pg8::Unit& u, int wr, int wc, int fr, int fq, LAS unsigned char* lds, int wid, int lane) const {
;     ...
;         if (wid == 0) {
;             unsigned sp = 0;
;             while ((unsigned)__builtin_amdgcn_readfirstlane(__hip_atomic_load(cnt + 64 * u.pm, __ATOMIC_RELAXED, __HIP_MEMORY_SCOPE_AGENT)) < 32u) { if (++sp > (1u << 20)) break; }
;             __builtin_amdgcn_fence(__ATOMIC_ACQUIRE, "agent");
;         }
.LBB0_1436:
	global_load_dword v18, v161, s[12:13] sc1
	s_waitcnt vmcnt(0)
	v_readfirstlane_b32 s25, v18
	s_cmp_gt_u32 s25, 31
	s_cselect_b64 s[34:35], -1, 0
	s_add_i32 s58, s24, 1
	s_cmp_gt_u32 s24, 0xfffff
	s_cselect_b64 s[24:25], -1, 0
	s_or_b64 s[24:25], s[34:35], s[24:25]
	s_andn2_b64 vcc, exec, s[24:25]
	s_mov_b32 s24, s58
	s_cbranch_vccnz .LBB0_1436
	buffer_inv sc0
